# spatial-gating phase: next tile operand loads prefetched during this tile's MFMA and epilogue; flat to global; batched LDS reads in the inner loop
# speedup vs baseline: 1.0203x; 1.0074x over previous
; #define LAS __attribute__((address_space(3)))
; __device__ __forceinline__ int tid_opaque() { int t = threadIdx.x; asm volatile("" : "+v"(t)); return t; }
; __device__ __forceinline__ int sgpr_opaque(int x) { asm volatile("" : "+s"(x)); return x; }
; #define INP(i) ((const float*)ldp(T, (i)))
; __device__ __forceinline__ void spatial_phase(const PT& T, int a, LAS unsigned char* lds, int vc) {
;     const int tid = tid_opaque(), lane = tid & 63, wid = __builtin_amdgcn_readfirstlane(tid >> 6), fr = lane & 15, fq = lane >> 4;
;     const bf16_t* __restrict__ Z = (const bf16_t*)((unsigned char*)OUTP); bf16_t* __restrict__ Y = (bf16_t*)(WSP + WS_T2);
;     const float* __restrict__ vst = (const float*)(WSP + WS_VST + (size_t)a * MiB);
;     const float* __restrict__ gv = INP(5) + a * D; const float* __restrict__ bs = INP(7) + a * D;
;     const bf16_t* __restrict__ Wm = (const bf16_t*)(WSP + WS_W) + WO_A_S0 + (size_t)a * WO_A_STRIDE;
;     constexpr int LDW = 136;
;     LAS bf16_t* sW = (LAS bf16_t*)lds; LAS bf16_t* sV = (LAS bf16_t*)(lds + 128 * LDW * 2);
;     const int R8 = sgpr_opaque(gridDim.x) >> 3, vx = sgpr_opaque(vc) & 7, vr = sgpr_opaque(vc) >> 3;
;     const int wi = wid >> 2, wc = wid & 3, ib = wi * 64, cb = wc * 32;
;     const int jq = tid >> 4, c8 = (tid & 15) * 8;
;     for (int ti = vr; ti < 256; ti += R8) {
;         const int t = 256 * vx + ti, nb = t >> 3, g = t & 7;
;         u32x4 wreg[4], vreg[4]; f32x4 p1[4], p2[4];
; #pragma unroll
;         for (int q = 0; q < 4; ++q) { const int j = jq + 32 * q; const size_t row = (size_t)nb * 128 + j;
;             wreg[q] = *(const u32x4*)(Wm + (size_t)g * 16384 + j * 128 + c8);
;             vreg[q] = *(const u32x4*)(Z + row * 2048 + 1024 + g * 128 + c8);
;             p1[q] = *(const f32x4*)(vst + 8 * row); p2[q] = *(const f32x4*)(vst + 8 * row + 4); }
;         const f32x4 g0 = *(const f32x4*)(gv + g * 128 + c8), g1 = *(const f32x4*)(gv + g * 128 + c8 + 4);
.LBB0_795:
	v_readlane_b32 s0, v254, 8
	v_mov_b32_e32 v0, v220
	v_readlane_b32 s4, v254, 13
	v_mov_b32_e32 v2, s0
	s_waitcnt lgkmcnt(0)
	ds_read2_b64 v[2:5], v2 offset1:1
	v_readlane_b32 s0, v254, 12
	s_mov_b32 s15, s68
	v_readfirstlane_b32 s10, v0
	v_mov_b32_e32 v6, s0
	ds_read_b64 v[6:7], v6
	s_waitcnt lgkmcnt(0)
	v_readfirstlane_b32 s0, v2
	v_mov_b32_e32 v2, s4
	v_readfirstlane_b32 s1, v3
	ds_read_b64 v[2:3], v2
	v_readlane_b32 s4, v254, 22
	s_mov_b32 s18, s4
	s_ashr_i32 s4, s4, 3
	v_readfirstlane_b32 s16, v5
	v_readfirstlane_b32 s19, v4
	v_readfirstlane_b32 s11, v7
	v_readfirstlane_b32 s17, v6
	s_waitcnt lgkmcnt(0)
	v_readfirstlane_b32 s9, v3
	s_cmpk_gt_i32 s4, 0xff
	v_readfirstlane_b32 s8, v2
	s_cbranch_scc1 .LBB0_800
	s_add_u32 s5, s19, 0x15000000
	v_readlane_b32 s6, v254, 27
	s_addc_u32 s14, s16, 0
	v_readlane_b32 s7, v254, 28
	s_mov_b32 s28, s6
	s_ashr_i32 s29, s6, 31
	s_lshl_b64 s[6:7], s[28:29], 20
	s_add_u32 s6, s19, s6
	s_addc_u32 s7, s16, s7
	s_add_u32 s6, s6, 0x19500000
	s_addc_u32 s7, s7, 0
	s_lshl_b32 s20, s28, 10
	s_ashr_i32 s21, s20, 31
	s_lshl_b64 s[20:21], s[20:21], 2
	s_add_u32 s8, s8, s20
	s_addc_u32 s9, s9, s21
	s_lshr_b32 s22, s10, 1
	s_ashr_i32 s25, s10, 2
	s_ashr_i32 s15, s15, 3
	s_and_b32 s24, s22, 0x60
	s_and_b32 s26, s25, 0xffffffc0
	s_mul_i32 s22, s28, 0x640000
	s_mul_hi_i32 s23, s28, 0x640000
	s_add_u32 s22, s19, s22
	s_addc_u32 s23, s16, s23
	s_add_u32 s20, s17, s20
	s_addc_u32 s21, s11, s21
	s_lshl_b32 s11, s18, 8
	v_lshlrev_b32_e32 v2, 3, v0
	s_and_b32 s16, s11, 0x700
	v_ashrrev_i32_e32 v34, 4, v0
	v_and_b32_e32 v2, 0x78, v2
	s_cmpk_lt_u32 s10, 0x100
	s_movk_i32 s11, 0x110
	v_bfe_u32 v3, v0, 4, 2
	v_and_b32_e32 v12, 15, v0
	v_lshlrev_b32_e32 v0, 1, v2
	s_cselect_b32 s17, 2, 4
	v_mul_lo_u32 v6, v34, s11
	s_and_b32 s10, s10, 0xc0
	v_lshl_add_u64 v[4:5], s[22:23], 0, v[0:1]
	v_add3_u32 v91, 0, v0, v6
	v_mov_b32_e32 v0, s10
	s_movk_i32 s10, 0x880
	v_or_b32_e32 v40, s26, v12
	v_mad_u32_u24 v0, v3, s10, v0
	v_ashrrev_i32_e32 v41, 31, v40
	v_lshl_or_b32 v0, v12, 1, v0
	v_readlane_b32 s10, v254, 14
	v_lshlrev_b64 v[56:57], 12, v[40:41]
	v_lshlrev_b64 v[64:65], 11, v[40:41]
	v_add_u32_e32 v41, s10, v0
	s_lshr_b32 s10, s25, 6
	s_mov_b64 s[18:19], 0xa00000
	s_mulk_i32 s10, 0x4400
	v_lshl_add_u64 v[36:37], v[4:5], 0, s[18:19]
	v_lshlrev_b32_e32 v4, 2, v2
	v_mov_b32_e32 v5, v1
	v_add_u32_e32 v44, 32, v34
	v_add_u32_e32 v48, 64, v34
	v_add_u32_e32 v52, 0x60, v34
	v_or_b32_e32 v6, 16, v40
	v_or_b32_e32 v8, 32, v40
	v_or_b32_e32 v10, 48, v40
	v_mov_b32_e32 v0, s10
	v_lshl_add_u64 v[38:39], s[20:21], 0, v[4:5]
	v_lshlrev_b32_e32 v4, 2, v3
	v_lshlrev_b32_e32 v5, 4, v3
	v_lshlrev_b32_e32 v42, 7, v34
	v_lshlrev_b32_e32 v46, 7, v44
	v_lshlrev_b32_e32 v50, 7, v48
	v_lshlrev_b32_e32 v54, 7, v52
	v_ashrrev_i32_e32 v7, 31, v6
	v_ashrrev_i32_e32 v9, 31, v8
	v_ashrrev_i32_e32 v11, 31, v10
	v_mad_u32_u24 v0, v12, s11, v0
	v_or_b32_e32 v90, s24, v4
	v_ashrrev_i32_e32 v35, 31, v34
	v_ashrrev_i32_e32 v43, 31, v42
	v_ashrrev_i32_e32 v45, 31, v44
	v_ashrrev_i32_e32 v47, 31, v46
	v_ashrrev_i32_e32 v49, 31, v48
	v_ashrrev_i32_e32 v51, 31, v50
	v_ashrrev_i32_e32 v53, 31, v52
	v_ashrrev_i32_e32 v55, 31, v54
	v_lshlrev_b64 v[58:59], 12, v[6:7]
	v_lshlrev_b64 v[60:61], 12, v[8:9]
	v_lshlrev_b64 v[62:63], 12, v[10:11]
	v_lshlrev_b64 v[66:67], 11, v[6:7]
	v_lshlrev_b64 v[68:69], 11, v[8:9]
	v_lshlrev_b64 v[70:71], 11, v[10:11]
	v_add3_u32 v92, v0, v5, 0
	v_lshlrev_b32_e32 v0, 1, v2
	s_lshl_b32 s18, s24, 1
	v_lshlrev_b32_e32 v72, 1, v4
	s_add_i32 s10, s4, s16
	s_ashr_i32 s10, s10, 3
	s_ashr_i32 s11, s10, 31
	s_lshl_b64 s[20:21], s[10:11], 7
	v_lshl_add_u64 v[120:121], s[20:21], 0, v[34:35]
	v_lshlrev_b64 v[122:123], 5, v[120:121]
	v_lshl_add_u64 v[122:123], s[6:7], 0, v[122:123]
	global_load_dwordx4 v[140:143], v[122:123], off
	global_load_dwordx4 v[144:147], v[122:123], off offset:16
	s_and_b32 s19, s4, 7
	s_lshl_b32 s46, s19, 15
	v_lshlrev_b64 v[120:121], 12, v[120:121]
	v_lshl_add_u64 v[124:125], v[36:37], 0, s[46:47]
	v_lshl_add_u64 v[120:121], s[0:1], 0, v[120:121]
	s_lshl_b32 s46, s19, 8
	v_lshl_add_u64 v[120:121], v[120:121], 0, s[46:47]
	v_lshl_add_u64 v[120:121], v[120:121], 0, v[0:1]
	global_load_dwordx4 v[148:151], v[120:121], off offset:2048
	s_mov_b32 s23, s47
	s_lshl_b32 s22, s19, 9
	v_lshl_add_u64 v[120:121], v[38:39], 0, s[22:23]
	global_load_dwordx4 v[128:131], v[120:121], off
	s_nop 0
	global_load_dwordx4 v[120:123], v[120:121], off offset:16
	v_lshl_add_u64 v[126:127], v[42:43], 1, v[124:125]
	v_lshl_add_u64 v[132:133], v[46:47], 1, v[124:125]
	v_lshl_add_u64 v[168:169], s[20:21], 0, v[44:45]
	global_load_dwordx4 v[152:155], v[126:127], off
	global_load_dwordx4 v[156:159], v[132:133], off
	v_lshlrev_b64 v[126:127], 5, v[168:169]
	v_lshl_add_u64 v[126:127], s[6:7], 0, v[126:127]
	global_load_dwordx4 v[160:163], v[126:127], off
	v_lshl_add_u64 v[134:135], v[50:51], 1, v[124:125]
	v_lshl_add_u64 v[124:125], v[54:55], 1, v[124:125]
	global_load_dwordx4 v[136:139], v[134:135], off
	global_load_dwordx4 v[164:167], v[126:127], off offset:16
	s_nop 0
	global_load_dwordx4 v[124:127], v[124:125], off
	v_lshlrev_b64 v[168:169], 12, v[168:169]
	v_lshl_add_u64 v[168:169], s[0:1], 0, v[168:169]
	v_lshl_add_u64 v[132:133], s[20:21], 0, v[48:49]
	v_lshl_add_u64 v[168:169], v[168:169], 0, s[46:47]
	v_lshlrev_b64 v[170:171], 12, v[132:133]
	v_lshl_add_u64 v[168:169], v[168:169], 0, v[0:1]
	v_lshl_add_u64 v[174:175], s[0:1], 0, v[170:171]
	global_load_dwordx4 v[168:171], v[168:169], off offset:2048
	v_lshl_add_u64 v[134:135], s[20:21], 0, v[52:53]
	v_lshlrev_b64 v[132:133], 5, v[132:133]
	v_lshlrev_b64 v[172:173], 12, v[134:135]
	v_lshl_add_u64 v[132:133], s[6:7], 0, v[132:133]
	v_lshl_add_u64 v[180:181], s[0:1], 0, v[172:173]
	v_lshl_add_u64 v[188:189], v[174:175], 0, s[46:47]
	global_load_dwordx4 v[172:175], v[132:133], off
	global_load_dwordx4 v[176:179], v[132:133], off offset:16
	v_lshlrev_b64 v[134:135], 5, v[134:135]
	v_lshl_add_u64 v[134:135], s[6:7], 0, v[134:135]
	v_lshl_add_u64 v[132:133], v[180:181], 0, s[46:47]
	global_load_dwordx4 v[180:183], v[134:135], off
	global_load_dwordx4 v[184:187], v[134:135], off offset:16
	v_lshl_add_u64 v[134:135], v[188:189], 0, v[0:1]
	v_lshl_add_u64 v[132:133], v[132:133], 0, v[0:1]
	global_load_dwordx4 v[188:191], v[134:135], off offset:2048
	s_nop 0
	global_load_dwordx4 v[132:135], v[132:133], off offset:2048
; #define LAS __attribute__((address_space(3)))
; __device__ __forceinline__ unsigned pk2(float lo, float hi) { return pg8::cvt_pk_bf16(lo, hi); }
; __device__ __forceinline__ void spatial_phase(const PT& T, int a, LAS unsigned char* lds, int vc) {
;     ...
;     for (int ti = vr; ti < 256; ti += R8) {
;         const int t = 256 * vx + ti, nb = t >> 3, g = t & 7;
;         u32x4 wreg[4], vreg[4]; f32x4 p1[4], p2[4];
; #pragma unroll
;         for (int q = 0; q < 4; ++q) { const int j = jq + 32 * q; const size_t row = (size_t)nb * 128 + j;
;             wreg[q] = *(const u32x4*)(Wm + (size_t)g * 16384 + j * 128 + c8);
;             vreg[q] = *(const u32x4*)(Z + row * 2048 + 1024 + g * 128 + c8);
;             p1[q] = *(const f32x4*)(vst + 8 * row); p2[q] = *(const f32x4*)(vst + 8 * row + 4); }
;         const f32x4 g0 = *(const f32x4*)(gv + g * 128 + c8), g1 = *(const f32x4*)(gv + g * 128 + c8 + 4);
; #pragma unroll
;         for (int q = 0; q < 4; ++q) { const int j = jq + 32 * q;
;             const float s1 = (p1[q].x + p1[q].y) + (p1[q].z + p1[q].w), s2 = (p2[q].x + p2[q].y) + (p2[q].z + p2[q].w);
;             const float mu = s1 * (1.0f / D); float var = s2 * (1.0f / D) - mu * mu; var = var > 0.f ? var : 0.f; const float rs = __builtin_amdgcn_rsqf(var + EPS);
;             const u32x4 raw = vreg[q];
;             u32x4 o; o.x = pk2((bflo(raw.x) - mu) * rs * g0.x, (bfhi(raw.x) - mu) * rs * g0.y); o.y = pk2((bflo(raw.y) - mu) * rs * g0.z, (bfhi(raw.y) - mu) * rs * g0.w);
;             o.z = pk2((bflo(raw.z) - mu) * rs * g1.x, (bfhi(raw.z) - mu) * rs * g1.y); o.w = pk2((bflo(raw.w) - mu) * rs * g1.z, (bfhi(raw.w) - mu) * rs * g1.w);
;             *(LAS u32x4*)(sV + j * LDW + c8) = o; *(LAS u32x4*)(sW + j * LDW + c8) = wreg[q]; }
.LBB0_797:
	s_add_i32 s10, s4, s16
	s_ashr_i32 s10, s10, 3
	s_ashr_i32 s11, s10, 31
	s_and_b32 s19, s4, 7
	s_lshl_b32 s46, s19, 8
	s_mov_b32 s20, 0x3a800000
	s_lshl_b32 s19, s19, 7
	s_waitcnt vmcnt(0) lgkmcnt(0)
	v_mov_b32_e32 v192, v141
	v_mov_b32_e32 v193, v142
	v_mov_b32_e32 v141, v143
	v_pk_add_f32 v[140:141], v[192:193], v[140:141]
	v_add_f32_e32 v142, v144, v145
	v_add_f32_e32 v144, v146, v147
	v_mov_b32_e32 v143, v140
	v_mov_b32_e32 v145, v141
	v_pk_add_f32 v[140:141], v[142:143], v[144:145]
	v_lshlrev_b32_e32 v146, 16, v148
	v_pk_mul_f32 v[142:143], v[140:141], s[20:21] op_sel_hi:[1,0]
	v_and_b32_e32 v147, 0xffff0000, v148
	v_fma_f32 v140, -v143, v143, v142
	v_max_f32_e32 v140, 0, v140
	v_add_f32_e32 v140, 0x358637bd, v140
	v_rsq_f32_e32 v145, v140
	v_lshlrev_b32_e32 v148, 16, v149
	v_lshlrev_b32_e32 v73, 16, v150
	v_and_b32_e32 v149, 0xffff0000, v149
	v_and_b32_e32 v150, 0xffff0000, v150
	v_sub_f32_e32 v141, v146, v143
	v_sub_f32_e32 v142, v147, v143
	v_sub_f32_e32 v144, v148, v143
	v_sub_f32_e32 v146, v73, v143
	v_sub_f32_e32 v140, v149, v143
	v_sub_f32_e32 v147, v150, v143
	v_mul_f32_e32 v141, v141, v145
	v_mul_f32_e32 v142, v142, v145
	v_mul_f32_e32 v144, v144, v145
	v_mul_f32_e32 v146, v146, v145
	v_mul_f32_e32 v140, v140, v145
	v_mul_f32_e32 v147, v147, v145
	v_mul_f32_e32 v141, v141, v128
	v_mul_f32_e32 v142, v142, v129
	v_mul_f32_e32 v144, v144, v130
	v_mul_f32_e32 v146, v146, v120
	v_mul_f32_e32 v148, v140, v131
	v_mul_f32_e32 v147, v147, v121
	v_cvt_pk_bf16_f32 v140, v141, v142
	v_cvt_pk_bf16_f32 v141, v144, v148
	v_cvt_pk_bf16_f32 v142, v146, v147
	v_lshlrev_b32_e32 v144, 16, v151
	v_and_b32_e32 v146, 0xffff0000, v151
	v_sub_f32_e32 v144, v144, v143
	v_sub_f32_e32 v143, v146, v143
	v_mul_f32_e32 v143, v143, v145
	v_mul_f32_e32 v144, v144, v145
	v_mul_f32_e32 v143, v143, v123
	v_mul_f32_e32 v144, v144, v122
	v_cvt_pk_bf16_f32 v143, v144, v143
	ds_write_b128 v91, v[140:143] offset:34816
	v_mov_b32_e32 v140, v161
	v_mov_b32_e32 v141, v162
	v_mov_b32_e32 v161, v163
	v_pk_add_f32 v[140:141], v[140:141], v[160:161]
	v_add_f32_e32 v142, v164, v165
	v_add_f32_e32 v144, v166, v167
	v_mov_b32_e32 v143, v140
	v_mov_b32_e32 v145, v141
	v_pk_add_f32 v[140:141], v[142:143], v[144:145]
	ds_write_b128 v91, v[152:155]
	v_pk_mul_f32 v[142:143], v[140:141], s[20:21] op_sel_hi:[1,0]
	v_and_b32_e32 v141, 0xffff0000, v168
	v_fma_f32 v140, -v143, v143, v142
	v_max_f32_e32 v140, 0, v140
	v_add_f32_e32 v140, 0x358637bd, v140
	v_rsq_f32_e32 v144, v140
	v_lshlrev_b32_e32 v140, 16, v168
	v_sub_f32_e32 v140, v140, v143
	v_sub_f32_e32 v141, v141, v143
	v_mul_f32_e32 v140, v140, v144
	v_mul_f32_e32 v141, v141, v144
	v_mul_f32_e32 v140, v128, v140
	v_mul_f32_e32 v141, v129, v141
	v_cvt_pk_bf16_f32 v140, v140, v141
	v_lshlrev_b32_e32 v141, 16, v169
	v_and_b32_e32 v142, 0xffff0000, v169
	v_sub_f32_e32 v141, v141, v143
	v_sub_f32_e32 v142, v142, v143
	v_mul_f32_e32 v141, v141, v144
	v_mul_f32_e32 v142, v142, v144
	v_mul_f32_e32 v141, v130, v141
	v_mul_f32_e32 v142, v131, v142
	v_cvt_pk_bf16_f32 v141, v141, v142
	v_lshlrev_b32_e32 v142, 16, v170
	v_and_b32_e32 v145, 0xffff0000, v170
	v_sub_f32_e32 v142, v142, v143
	v_sub_f32_e32 v145, v145, v143
	v_mul_f32_e32 v142, v142, v144
	v_mul_f32_e32 v145, v145, v144
	v_mul_f32_e32 v142, v142, v120
	v_mul_f32_e32 v145, v145, v121
	v_cvt_pk_bf16_f32 v142, v142, v145
	v_lshlrev_b32_e32 v145, 16, v171
	v_and_b32_e32 v146, 0xffff0000, v171
	v_sub_f32_e32 v145, v145, v143
	v_sub_f32_e32 v143, v146, v143
	v_mul_f32_e32 v143, v143, v144
	v_mul_f32_e32 v145, v145, v144
	v_mul_f32_e32 v143, v143, v123
	v_mul_f32_e32 v145, v145, v122
	v_cvt_pk_bf16_f32 v143, v145, v143
	ds_write_b128 v91, v[140:143] offset:43520
	v_mov_b32_e32 v140, v173
	v_mov_b32_e32 v141, v174
	v_mov_b32_e32 v173, v175
	v_pk_add_f32 v[140:141], v[140:141], v[172:173]
	v_add_f32_e32 v142, v176, v177
	v_add_f32_e32 v144, v178, v179
	v_mov_b32_e32 v143, v140
	v_mov_b32_e32 v145, v141
	v_pk_add_f32 v[140:141], v[142:143], v[144:145]
	ds_write_b128 v91, v[156:159] offset:8704
	v_pk_mul_f32 v[142:143], v[140:141], s[20:21] op_sel_hi:[1,0]
	v_and_b32_e32 v141, 0xffff0000, v188
	v_fma_f32 v140, -v143, v143, v142
	v_max_f32_e32 v140, 0, v140
	v_add_f32_e32 v140, 0x358637bd, v140
	v_rsq_f32_e32 v144, v140
	v_lshlrev_b32_e32 v140, 16, v188
	v_sub_f32_e32 v140, v140, v143
	v_sub_f32_e32 v141, v141, v143
	v_mul_f32_e32 v140, v140, v144
	v_mul_f32_e32 v141, v141, v144
	v_mul_f32_e32 v140, v128, v140
	v_mul_f32_e32 v141, v129, v141
	v_cvt_pk_bf16_f32 v140, v140, v141
	v_lshlrev_b32_e32 v141, 16, v189
	v_and_b32_e32 v142, 0xffff0000, v189
	v_sub_f32_e32 v141, v141, v143
	v_sub_f32_e32 v142, v142, v143
	v_mul_f32_e32 v141, v141, v144
	v_mul_f32_e32 v142, v142, v144
	v_mul_f32_e32 v141, v130, v141
	v_mul_f32_e32 v142, v131, v142
	v_cvt_pk_bf16_f32 v141, v141, v142
	v_lshlrev_b32_e32 v142, 16, v190
	v_and_b32_e32 v145, 0xffff0000, v190
	v_sub_f32_e32 v142, v142, v143
	v_sub_f32_e32 v145, v145, v143
	v_mul_f32_e32 v142, v142, v144
	v_mul_f32_e32 v145, v145, v144
	v_mul_f32_e32 v142, v120, v142
	v_mul_f32_e32 v145, v121, v145
	v_cvt_pk_bf16_f32 v142, v142, v145
	v_lshlrev_b32_e32 v145, 16, v191
	v_and_b32_e32 v146, 0xffff0000, v191
	v_sub_f32_e32 v145, v145, v143
	v_sub_f32_e32 v143, v146, v143
	v_mul_f32_e32 v143, v143, v144
	v_mul_f32_e32 v145, v145, v144
	v_mul_f32_e32 v143, v123, v143
	v_mul_f32_e32 v145, v122, v145
	v_cvt_pk_bf16_f32 v143, v145, v143
	ds_write_b128 v91, v[140:143] offset:52224
	v_mov_b32_e32 v140, v181
	v_mov_b32_e32 v141, v182
	v_mov_b32_e32 v181, v183
	v_pk_add_f32 v[140:141], v[140:141], v[180:181]
	v_add_f32_e32 v142, v184, v185
; #define LAS __attribute__((address_space(3)))
; __device__ __forceinline__ unsigned pk2(float lo, float hi) { return pg8::cvt_pk_bf16(lo, hi); }
; __device__ __forceinline__ void spatial_phase(const PT& T, int a, LAS unsigned char* lds, int vc) {
;     ...
;         for (int q = 0; q < 4; ++q) { const int j = jq + 32 * q; const size_t row = (size_t)nb * 128 + j;
;             wreg[q] = *(const u32x4*)(Wm + (size_t)g * 16384 + j * 128 + c8);
;             vreg[q] = *(const u32x4*)(Z + row * 2048 + 1024 + g * 128 + c8);
;             p1[q] = *(const f32x4*)(vst + 8 * row); p2[q] = *(const f32x4*)(vst + 8 * row + 4); }
;         const f32x4 g0 = *(const f32x4*)(gv + g * 128 + c8), g1 = *(const f32x4*)(gv + g * 128 + c8 + 4);
;     ...
;             const float s1 = (p1[q].x + p1[q].y) + (p1[q].z + p1[q].w), s2 = (p2[q].x + p2[q].y) + (p2[q].z + p2[q].w);
;             const float mu = s1 * (1.0f / D); float var = s2 * (1.0f / D) - mu * mu; var = var > 0.f ? var : 0.f; const float rs = __builtin_amdgcn_rsqf(var + EPS);
;             const u32x4 raw = vreg[q];
;             u32x4 o; o.x = pk2((bflo(raw.x) - mu) * rs * g0.x, (bfhi(raw.x) - mu) * rs * g0.y); o.y = pk2((bflo(raw.y) - mu) * rs * g0.z, (bfhi(raw.y) - mu) * rs * g0.w);
;             o.z = pk2((bflo(raw.z) - mu) * rs * g1.x, (bfhi(raw.z) - mu) * rs * g1.y); o.w = pk2((bflo(raw.w) - mu) * rs * g1.z, (bfhi(raw.w) - mu) * rs * g1.w);
;             *(LAS u32x4*)(sV + j * LDW + c8) = o; *(LAS u32x4*)(sW + j * LDW + c8) = wreg[q]; }
;         u32x2 uu[4][2]; float bsv[4];
; #pragma unroll
;         for (int mt = 0; mt < 4; ++mt) { const int i = ib + 16 * mt + fr; bsv[mt] = bs[g * 128 + i];
; #pragma unroll
;             for (int n = 0; n < 2; ++n) uu[mt][n] = *(const u32x2*)(Z + ((size_t)nb * 128 + i) * 2048 + g * 128 + cb + 16 * n + 4 * fq); }
;         __syncthreads();
;         f32x4 acc[4][2];
; #pragma unroll
;         for (int mt = 0; mt < 4; ++mt)
; #pragma unroll
;             for (int n = 0; n < 2; ++n) acc[mt][n] = (f32x4){0.f, 0.f, 0.f, 0.f};
	v_add_f32_e32 v144, v186, v187
	v_mov_b32_e32 v143, v140
	v_mov_b32_e32 v145, v141
	v_pk_add_f32 v[140:141], v[142:143], v[144:145]
	ds_write_b128 v91, v[136:139] offset:17408
	v_pk_mul_f32 v[140:141], v[140:141], s[20:21] op_sel_hi:[1,0]
	v_lshlrev_b32_e32 v136, 16, v132
	v_fma_f32 v140, -v141, v141, v140
	v_max_f32_e32 v140, 0, v140
	v_add_f32_e32 v140, 0x358637bd, v140
	v_rsq_f32_e32 v140, v140
	v_and_b32_e32 v132, 0xffff0000, v132
	v_sub_f32_e32 v136, v136, v141
	v_sub_f32_e32 v132, v132, v141
	v_mul_f32_e32 v136, v136, v140
	v_mul_f32_e32 v132, v132, v140
	v_mul_f32_e32 v128, v128, v136
	v_mul_f32_e32 v129, v129, v132
	v_cvt_pk_bf16_f32 v128, v128, v129
	v_lshlrev_b32_e32 v129, 16, v133
	v_sub_f32_e32 v129, v129, v141
	v_mul_f32_e32 v129, v129, v140
	v_mul_f32_e32 v129, v130, v129
	v_and_b32_e32 v130, 0xffff0000, v133
	v_sub_f32_e32 v130, v130, v141
	v_mul_f32_e32 v130, v130, v140
	v_mul_f32_e32 v130, v131, v130
	v_cvt_pk_bf16_f32 v129, v129, v130
	v_lshlrev_b32_e32 v130, 16, v134
	v_sub_f32_e32 v130, v130, v141
	v_mul_f32_e32 v130, v130, v140
	v_mul_f32_e32 v120, v120, v130
	v_and_b32_e32 v130, 0xffff0000, v134
	v_sub_f32_e32 v130, v130, v141
	s_lshl_b64 s[20:21], s[10:11], 19
	v_mul_f32_e32 v130, v130, v140
	s_add_u32 s20, s0, s20
	v_mul_f32_e32 v121, v121, v130
	s_addc_u32 s21, s1, s21
	v_cvt_pk_bf16_f32 v130, v120, v121
	v_lshlrev_b32_e32 v120, 16, v135
	v_and_b32_e32 v121, 0xffff0000, v135
	s_add_u32 s20, s20, s46
	v_sub_f32_e32 v120, v120, v141
	v_sub_f32_e32 v121, v121, v141
	s_addc_u32 s21, s21, 0
	v_mul_f32_e32 v120, v120, v140
	v_mul_f32_e32 v121, v121, v140
	s_add_u32 s20, s20, s18
	v_mul_f32_e32 v120, v122, v120
	v_mul_f32_e32 v121, v123, v121
	s_addc_u32 s21, s21, 0
	v_mov_b32_e32 v73, v1
	v_cvt_pk_bf16_f32 v131, v120, v121
	ds_write_b128 v91, v[128:131] offset:60928
	ds_write_b128 v91, v[124:127] offset:26112
	v_lshl_add_u64 v[2:3], s[20:21], 0, v[72:73]
	v_add_u32_e32 v4, s19, v40
	v_ashrrev_i32_e32 v5, 31, v4
	v_lshl_add_u64 v[6:7], v[2:3], 0, v[56:57]
	v_lshl_add_u64 v[4:5], v[4:5], 2, s[8:9]
	v_lshl_add_u64 v[8:9], v[2:3], 0, v[58:59]
	global_load_dwordx2 v[88:89], v[6:7], off
	global_load_dwordx2 v[86:87], v[6:7], off offset:32
	global_load_dwordx2 v[84:85], v[8:9], off
	global_load_dwordx2 v[82:83], v[8:9], off offset:32
	v_lshl_add_u64 v[6:7], v[2:3], 0, v[60:61]
	global_load_dword v95, v[4:5], off
	global_load_dword v94, v[4:5], off offset:64
	global_load_dword v93, v[4:5], off offset:128
	global_load_dword v73, v[4:5], off offset:192
	v_lshl_add_u64 v[2:3], v[2:3], 0, v[62:63]
	global_load_dwordx2 v[80:81], v[6:7], off
	global_load_dwordx2 v[78:79], v[6:7], off offset:32
	global_load_dwordx2 v[76:77], v[2:3], off
	global_load_dwordx2 v[74:75], v[2:3], off offset:32
	v_mov_b32_e32 v2, 0
	v_mov_b32_e32 v96, v92
	v_mov_b32_e32 v97, v41
	s_mov_b32 s20, s17
	v_mov_b32_e32 v3, v2
	v_mov_b32_e32 v4, v2
	v_mov_b32_e32 v5, v2
	v_mov_b32_e32 v6, v2
	v_mov_b32_e32 v7, v2
	v_mov_b32_e32 v8, v2
	v_mov_b32_e32 v9, v2
	v_mov_b32_e32 v10, v2
	v_mov_b32_e32 v11, v2
	v_mov_b32_e32 v12, v2
	v_mov_b32_e32 v13, v2
	v_mov_b32_e32 v14, v2
	v_mov_b32_e32 v15, v2
	v_mov_b32_e32 v16, v2
	v_mov_b32_e32 v17, v2
	v_mov_b32_e32 v18, v2
	v_mov_b32_e32 v19, v2
	v_mov_b32_e32 v20, v2
	v_mov_b32_e32 v21, v2
	v_mov_b32_e32 v22, v2
	v_mov_b32_e32 v23, v2
	v_mov_b32_e32 v24, v2
	v_mov_b32_e32 v25, v2
	v_mov_b32_e32 v26, v2
	v_mov_b32_e32 v27, v2
	v_mov_b32_e32 v28, v2
	v_mov_b32_e32 v29, v2
	v_mov_b32_e32 v30, v2
	v_mov_b32_e32 v31, v2
	v_mov_b32_e32 v32, v2
	v_mov_b32_e32 v33, v2
	s_waitcnt lgkmcnt(0)
	s_barrier
	s_add_i32 s24, s4, s15
	s_cmpk_gt_i32 s24, 0xff
	s_cbranch_scc1 .Lsp_nopf
	s_mov_b32 vcc_hi, 0
	s_add_i32 s26, s24, s16
	s_ashr_i32 s28, s26, 3
	s_ashr_i32 s29, s28, 31
	s_lshl_b64 s[28:29], s[28:29], 7
	v_lshl_add_u64 v[120:121], s[28:29], 0, v[34:35]
	v_lshlrev_b64 v[122:123], 5, v[120:121]
	v_lshl_add_u64 v[122:123], s[6:7], 0, v[122:123]
	global_load_dwordx4 v[140:143], v[122:123], off
	global_load_dwordx4 v[144:147], v[122:123], off offset:16
	s_and_b32 s25, s24, 7
	s_lshl_b32 vcc_lo, s25, 15
	v_lshlrev_b64 v[120:121], 12, v[120:121]
	v_lshl_add_u64 v[124:125], v[36:37], 0, vcc
	v_lshl_add_u64 v[120:121], s[0:1], 0, v[120:121]
	s_lshl_b32 vcc_lo, s25, 8
	v_lshl_add_u64 v[120:121], v[120:121], 0, vcc
	v_lshl_add_u64 v[120:121], v[120:121], 0, v[0:1]
	global_load_dwordx4 v[148:151], v[120:121], off offset:2048
	s_lshl_b32 vcc_lo, s25, 9
	v_lshl_add_u64 v[120:121], v[38:39], 0, vcc
	s_lshl_b32 vcc_lo, s25, 8
	global_load_dwordx4 v[128:131], v[120:121], off
	s_nop 0
	global_load_dwordx4 v[120:123], v[120:121], off offset:16
	v_lshl_add_u64 v[126:127], v[42:43], 1, v[124:125]
	v_lshl_add_u64 v[132:133], v[46:47], 1, v[124:125]
	v_lshl_add_u64 v[168:169], s[28:29], 0, v[44:45]
	global_load_dwordx4 v[152:155], v[126:127], off
	global_load_dwordx4 v[156:159], v[132:133], off
	v_lshlrev_b64 v[126:127], 5, v[168:169]
	v_lshl_add_u64 v[126:127], s[6:7], 0, v[126:127]
	global_load_dwordx4 v[160:163], v[126:127], off
	v_lshl_add_u64 v[134:135], v[50:51], 1, v[124:125]
	v_lshl_add_u64 v[124:125], v[54:55], 1, v[124:125]
	global_load_dwordx4 v[136:139], v[134:135], off
	global_load_dwordx4 v[164:167], v[126:127], off offset:16
	s_nop 0
	global_load_dwordx4 v[124:127], v[124:125], off
	v_lshlrev_b64 v[168:169], 12, v[168:169]
	v_lshl_add_u64 v[168:169], s[0:1], 0, v[168:169]
	v_lshl_add_u64 v[132:133], s[28:29], 0, v[48:49]
	v_lshl_add_u64 v[168:169], v[168:169], 0, vcc
	v_lshlrev_b64 v[170:171], 12, v[132:133]
	v_lshl_add_u64 v[168:169], v[168:169], 0, v[0:1]
	v_lshl_add_u64 v[174:175], s[0:1], 0, v[170:171]
	global_load_dwordx4 v[168:171], v[168:169], off offset:2048
	v_lshl_add_u64 v[134:135], s[28:29], 0, v[52:53]
	v_lshlrev_b64 v[132:133], 5, v[132:133]
	v_lshlrev_b64 v[172:173], 12, v[134:135]
	v_lshl_add_u64 v[132:133], s[6:7], 0, v[132:133]
	v_lshl_add_u64 v[180:181], s[0:1], 0, v[172:173]
	v_lshl_add_u64 v[188:189], v[174:175], 0, vcc
	global_load_dwordx4 v[172:175], v[132:133], off
	global_load_dwordx4 v[176:179], v[132:133], off offset:16
	v_lshlrev_b64 v[134:135], 5, v[134:135]
	v_lshl_add_u64 v[134:135], s[6:7], 0, v[134:135]
	v_lshl_add_u64 v[132:133], v[180:181], 0, vcc
	global_load_dwordx4 v[180:183], v[134:135], off
	global_load_dwordx4 v[184:187], v[134:135], off offset:16
	v_lshl_add_u64 v[134:135], v[188:189], 0, v[0:1]
	v_lshl_add_u64 v[132:133], v[132:133], 0, v[0:1]
	global_load_dwordx4 v[188:191], v[134:135], off offset:2048
	s_nop 0
	global_load_dwordx4 v[132:135], v[132:133], off offset:2048
; #define LAS __attribute__((address_space(3)))
; __device__ __forceinline__ unsigned pk2(float lo, float hi) { return pg8::cvt_pk_bf16(lo, hi); }
; __device__ __forceinline__ void spatial_phase(const PT& T, int a, LAS unsigned char* lds, int vc) {
;     ...
;         for (int kk = 0; kk < nk; ++kk) {
;             bf16x8 bfr[4], af[2];
; #pragma unroll
;             for (int mt = 0; mt < 4; ++mt) bfr[mt] = *(const LAS bf16x8*)(sW + (ib + 16 * mt + fr) * LDW + kk * 32 + 8 * fq);
; #pragma unroll
;             for (int n = 0; n < 2; ++n)
; #pragma unroll
;                 for (int e = 0; e < 8; ++e) af[n][e] = (short)sV[(kk * 32 + 8 * fq + e) * LDW + cb + 16 * n + fr];
; #pragma unroll
;             for (int mt = 0; mt < 4; ++mt)
; #pragma unroll
;                 for (int n = 0; n < 2; ++n) acc[mt][n] = __builtin_amdgcn_mfma_f32_16x16x32_bf16(af[n], bfr[mt], acc[mt][n], 0, 0, 0);
;         }
; #pragma unroll
;         for (int mt = 0; mt < 4; ++mt) { const int i = ib + 16 * mt + fr; const size_t row = (size_t)nb * 128 + i;
; #pragma unroll
;             for (int n = 0; n < 2; ++n) { const int c = g * 128 + cb + 16 * n + 4 * fq; const u32x2 u2 = uu[mt][n];
;                 u32x2 o; o.x = pk2(bflo(u2.x) * (acc[mt][n][0] + bsv[mt]), bfhi(u2.x) * (acc[mt][n][1] + bsv[mt])); o.y = pk2(bflo(u2.y) * (acc[mt][n][2] + bsv[mt]), bfhi(u2.y) * (acc[mt][n][3] + bsv[mt]));
;                 *(u32x2*)(Y + row * D + c) = o; } }
;         __syncthreads();
.Lsp_nopf:
.LBB0_798:
	ds_read_b128 v[98:101], v96
	ds_read_b128 v[202:205], v96 offset:4352
	ds_read_b128 v[206:209], v96 offset:8704
	ds_read_b128 v[210:213], v96 offset:13056
	ds_read_u16 v102, v97 offset:272
	ds_read_u16 v103, v97 offset:544
	ds_read_u16 v106, v97 offset:816
	ds_read_u16 v107, v97
	ds_read_u16 v110, v97 offset:848
	ds_read_u16 v111, v97 offset:576
	ds_read_u16 v112, v97 offset:304
	ds_read_u16 v113, v97 offset:32
	ds_read_u16 v104, v97 offset:1088
	ds_read_u16 v108, v97 offset:1360
	ds_read_u16 v105, v97 offset:1632
	ds_read_u16 v109, v97 offset:1904
	ds_read_u16 v114, v97 offset:1936
	ds_read_u16 v115, v97 offset:1664
	ds_read_u16 v116, v97 offset:1392
	ds_read_u16 v117, v97 offset:1120
	s_add_i32 s20, s20, -1
	s_waitcnt lgkmcnt(0)
	v_perm_b32 v105, v109, v105, s73
	v_perm_b32 v104, v108, v104, s73
	v_perm_b32 v103, v106, v103, s73
	v_perm_b32 v102, v102, v107, s73
	v_perm_b32 v109, v114, v115, s73
	v_perm_b32 v108, v116, v117, s73
	v_perm_b32 v107, v110, v111, s73
	v_perm_b32 v106, v112, v113, s73
	v_add_u32_e32 v97, 0x2200, v97
	v_add_u32_e32 v96, 64, v96
	s_cmp_eq_u32 s20, 0
	v_mfma_f32_16x16x32_bf16 v[30:33], v[102:105], v[98:101], v[30:33]
	v_mfma_f32_16x16x32_bf16 v[26:29], v[106:109], v[98:101], v[26:29]
	v_mfma_f32_16x16x32_bf16 v[22:25], v[102:105], v[202:205], v[22:25]
	v_mfma_f32_16x16x32_bf16 v[18:21], v[106:109], v[202:205], v[18:21]
	v_mfma_f32_16x16x32_bf16 v[14:17], v[102:105], v[206:209], v[14:17]
	v_mfma_f32_16x16x32_bf16 v[10:13], v[106:109], v[206:209], v[10:13]
	v_mfma_f32_16x16x32_bf16 v[6:9], v[102:105], v[210:213], v[6:9]
	v_mfma_f32_16x16x32_bf16 v[2:5], v[106:109], v[210:213], v[2:5]
	s_cbranch_scc0 .LBB0_798
	s_cmpk_gt_i32 s24, 0xff
	s_cbranch_scc1 .Lsp_w0
	s_waitcnt vmcnt(18)
	s_branch .Lsp_epi
.Lsp_w0:
	s_waitcnt vmcnt(0)
.Lsp_epi:
	v_lshlrev_b32_e32 v99, 16, v88
	v_add_f32_e32 v30, v95, v30
	v_and_b32_e32 v88, 0xffff0000, v88
	v_add_f32_e32 v31, v95, v31
	v_mul_f32_e32 v30, v30, v99
	v_mul_f32_e32 v31, v31, v88
	s_lshl_b64 s[10:11], s[10:11], 18
	v_cvt_pk_bf16_f32 v30, v30, v31
	v_lshlrev_b32_e32 v31, 16, v89
	v_add_f32_e32 v32, v95, v32
	s_add_u32 s10, s5, s10
	v_mul_f32_e32 v31, v32, v31
	v_and_b32_e32 v32, 0xffff0000, v89
	v_add_f32_e32 v33, v95, v33
	v_or_b32_e32 v98, s19, v90
	s_addc_u32 s11, s14, s11
	v_mul_f32_e32 v32, v33, v32
	v_lshl_add_u64 v[96:97], s[10:11], 0, v[64:65]
	v_cvt_pk_bf16_f32 v31, v31, v32
	v_lshlrev_b32_e32 v32, 1, v98
	v_mov_b32_e32 v33, v1
	v_lshl_add_u64 v[88:89], v[96:97], 0, v[32:33]
	global_store_dwordx2 v[88:89], v[30:31], off
	v_lshlrev_b32_e32 v30, 16, v86
	v_add_f32_e32 v26, v95, v26
	v_mul_f32_e32 v26, v26, v30
	v_and_b32_e32 v30, 0xffff0000, v86
	v_add_f32_e32 v27, v95, v27
	v_mul_f32_e32 v27, v27, v30
	v_cvt_pk_bf16_f32 v26, v26, v27
	v_lshlrev_b32_e32 v27, 16, v87
	v_add_f32_e32 v28, v95, v28
	v_mul_f32_e32 v27, v28, v27
	v_and_b32_e32 v28, 0xffff0000, v87
	v_add_f32_e32 v29, v95, v29
	v_mul_f32_e32 v28, v29, v28
	v_cvt_pk_bf16_f32 v27, v27, v28
	v_lshlrev_b32_e32 v28, 16, v84
	v_add_f32_e32 v22, v94, v22
	v_mul_f32_e32 v22, v22, v28
	v_and_b32_e32 v28, 0xffff0000, v84
	v_add_f32_e32 v23, v94, v23
	v_mul_f32_e32 v23, v23, v28
	global_store_dwordx2 v[88:89], v[26:27], off offset:32
	v_cvt_pk_bf16_f32 v22, v22, v23
	v_lshlrev_b32_e32 v23, 16, v85
	v_add_f32_e32 v24, v94, v24
	v_mul_f32_e32 v23, v24, v23
	v_and_b32_e32 v24, 0xffff0000, v85
	v_add_f32_e32 v25, v94, v25
	v_lshl_add_u64 v[26:27], s[10:11], 0, v[66:67]
	v_mul_f32_e32 v24, v25, v24
	v_cvt_pk_bf16_f32 v23, v23, v24
	v_lshl_add_u64 v[24:25], v[26:27], 0, v[32:33]
	global_store_dwordx2 v[24:25], v[22:23], off
	v_lshlrev_b32_e32 v22, 16, v82
	v_add_f32_e32 v18, v94, v18
	v_mul_f32_e32 v18, v18, v22
	v_and_b32_e32 v22, 0xffff0000, v82
	v_add_f32_e32 v19, v94, v19
	v_mul_f32_e32 v19, v19, v22
	v_cvt_pk_bf16_f32 v18, v18, v19
	v_lshlrev_b32_e32 v19, 16, v83
	v_add_f32_e32 v20, v94, v20
	v_mul_f32_e32 v19, v20, v19
	v_and_b32_e32 v20, 0xffff0000, v83
	v_add_f32_e32 v21, v94, v21
	v_mul_f32_e32 v20, v21, v20
	v_cvt_pk_bf16_f32 v19, v19, v20
	v_lshlrev_b32_e32 v20, 16, v80
	v_add_f32_e32 v14, v93, v14
	v_mul_f32_e32 v14, v14, v20
	v_and_b32_e32 v20, 0xffff0000, v80
	v_add_f32_e32 v15, v93, v15
	v_mul_f32_e32 v15, v15, v20
	global_store_dwordx2 v[24:25], v[18:19], off offset:32
	v_cvt_pk_bf16_f32 v14, v14, v15
	v_lshlrev_b32_e32 v15, 16, v81
	v_add_f32_e32 v16, v93, v16
	v_mul_f32_e32 v15, v16, v15
	v_and_b32_e32 v16, 0xffff0000, v81
	v_add_f32_e32 v17, v93, v17
	v_lshl_add_u64 v[18:19], s[10:11], 0, v[68:69]
	v_mul_f32_e32 v16, v17, v16
	v_cvt_pk_bf16_f32 v15, v15, v16
	v_lshl_add_u64 v[16:17], v[18:19], 0, v[32:33]
	global_store_dwordx2 v[16:17], v[14:15], off
	v_lshlrev_b32_e32 v14, 16, v78
	v_add_f32_e32 v10, v93, v10
	v_mul_f32_e32 v10, v10, v14
	v_and_b32_e32 v14, 0xffff0000, v78
	v_add_f32_e32 v11, v93, v11
	v_mul_f32_e32 v11, v11, v14
	v_cvt_pk_bf16_f32 v10, v10, v11
	v_lshlrev_b32_e32 v11, 16, v79
	v_add_f32_e32 v12, v93, v12
	v_mul_f32_e32 v11, v12, v11
	v_and_b32_e32 v12, 0xffff0000, v79
	v_add_f32_e32 v13, v93, v13
	v_mul_f32_e32 v12, v13, v12
	v_cvt_pk_bf16_f32 v11, v11, v12
	v_lshlrev_b32_e32 v12, 16, v76
	v_add_f32_e32 v6, v73, v6
	v_mul_f32_e32 v6, v6, v12
	v_and_b32_e32 v12, 0xffff0000, v76
	v_add_f32_e32 v7, v73, v7
	v_mul_f32_e32 v7, v7, v12
	global_store_dwordx2 v[16:17], v[10:11], off offset:32
	v_cvt_pk_bf16_f32 v6, v6, v7
	v_lshlrev_b32_e32 v7, 16, v77
	v_add_f32_e32 v8, v73, v8
	v_mul_f32_e32 v7, v8, v7
	v_and_b32_e32 v8, 0xffff0000, v77
	v_add_f32_e32 v9, v73, v9
	v_lshl_add_u64 v[10:11], s[10:11], 0, v[70:71]
	v_mul_f32_e32 v8, v9, v8
	v_cvt_pk_bf16_f32 v7, v7, v8
	v_lshl_add_u64 v[8:9], v[10:11], 0, v[32:33]
	global_store_dwordx2 v[8:9], v[6:7], off
	v_lshlrev_b32_e32 v6, 16, v74
	v_add_f32_e32 v2, v73, v2
	v_mul_f32_e32 v2, v2, v6
	v_and_b32_e32 v6, 0xffff0000, v74
	v_add_f32_e32 v3, v73, v3
	v_mul_f32_e32 v3, v3, v6
	v_cvt_pk_bf16_f32 v2, v2, v3
	v_lshlrev_b32_e32 v3, 16, v75
	v_add_f32_e32 v4, v73, v4
	s_add_i32 s4, s4, s15
	v_mul_f32_e32 v3, v4, v3
	v_and_b32_e32 v4, 0xffff0000, v75
	v_add_f32_e32 v5, v73, v5
	s_cmpk_gt_i32 s4, 0xff
	v_mul_f32_e32 v4, v5, v4
	v_cvt_pk_bf16_f32 v3, v3, v4
	global_store_dwordx2 v[8:9], v[2:3], off offset:32
	s_waitcnt lgkmcnt(0)
	s_barrier
	s_cbranch_scc0 .LBB0_797
